# v061 + mLSTM step C: per-row normaliser computed once per row via LDS scratch (bit-identical) and h tile written as dwords by lane pairing (16 ds_write_b32 instead of 32 ds_write_b16)
# speedup vs baseline: 1.0157x; 1.0157x over previous
; #define LAS __attribute__((address_space(3)))
; DI int opq(int x) { asm volatile("" : "+v"(x)); return x; }
; DI bf16x8 join4(const s16x4& lo, const s16x4& hi) { return __builtin_shufflevector(lo, hi, 0, 1, 2, 3, 4, 5, 6, 7); }
; #define MFMA32(a, b, c) __builtin_amdgcn_mfma_f32_32x32x16_bf16((a), (b), (c), 0, 0, 0)
; DI void phase_mlstm(const Params& p, unsigned char* shm, const int vb) {
;     ...
;             {
;                 const int lane = opq(threadIdx.x) & 63, l32 = lane & 31, hh = lane >> 5;
;                 const int qb = QI + l32 * RS + 8 * hh;
; #pragma unroll
;                 for (int ci = 0; ci < 8; ++ci) {
;                     s16x4 lo[2][2], hi[2][2];
; #pragma unroll
;                     for (int st = 0; st < 2; ++st)
; #pragma unroll
;                         for (int m2 = 0; m2 < 2; ++m2) { const int off = qb + 32 * m2 * RS + 64 * ci + 32 * st;
;                             lo[st][m2] = *(const LAS s16x4*)(lds + off); hi[st][m2] = *(const LAS s16x4*)(lds + off + 16); }
;                     const bf16x8 bf0 = pack_step<0>(C[ci]), bf1 = pack_step<1>(C[ci]);
;                     __builtin_amdgcn_sched_barrier(0);
; #pragma unroll
;                     for (int m2 = 0; m2 < 2; ++m2) acc2[m2] = MFMA32(join4(lo[0][m2], hi[0][m2]), bf0, acc2[m2]);
; #pragma unroll
;                     for (int m2 = 0; m2 < 2; ++m2) acc2[m2] = MFMA32(join4(lo[1][m2], hi[1][m2]), bf1, acc2[m2]);
;                     __builtin_amdgcn_sched_barrier(0);
;                 }
;             }
.LBB0_393:
	s_nop 4
	v_mov_b32_e32 v128, v192
	v_cvt_pk_bf16_f32 v136, v48, v49
	v_and_b32_e32 v129, 31, v128
	v_lshrrev_b32_e32 v128, 2, v128
	v_mul_u32_u24_e32 v129, 0x210, v129
	v_and_b32_e32 v128, 8, v128
	v_add3_u32 v170, 0, v129, v128
	v_add_u32_e32 v179, 0x4000, v170
	ds_read2_b64 v[128:131], v179 offset0:64 offset1:66
	s_waitcnt lgkmcnt(2)
	ds_read2_b64 v[132:135], v170 offset1:2
	ds_read2_b64 v[164:167], v170 offset0:4 offset1:6
	ds_read2_b64 v[180:183], v179 offset0:68 offset1:70
	v_cvt_pk_bf16_f32 v137, v50, v51
	v_cvt_pk_bf16_f32 v138, v52, v53
	v_cvt_pk_bf16_f32 v139, v54, v55
	v_cvt_pk_bf16_f32 v184, v56, v57
	v_cvt_pk_bf16_f32 v185, v58, v59
	v_cvt_pk_bf16_f32 v186, v60, v61
	v_cvt_pk_bf16_f32 v187, v62, v63
	s_waitcnt lgkmcnt(2)
	v_mfma_f32_32x32x16_bf16 v[144:159], v[132:135], v[136:139], 0
	v_mfma_f32_32x32x16_bf16 v[128:143], v[128:131], v[136:139], 0
	s_waitcnt lgkmcnt(1)
	v_mfma_f32_32x32x16_bf16 v[144:159], v[164:167], v[184:187], v[144:159]
	s_waitcnt lgkmcnt(0)
	v_mfma_f32_32x32x16_bf16 v[128:143], v[180:183], v[184:187], v[128:143]
	ds_read2_b64 v[164:167], v179 offset0:72 offset1:74
	ds_read2_b64 v[180:183], v170 offset0:8 offset1:10
	ds_read2_b64 v[184:187], v170 offset0:12 offset1:14
	ds_read2_b64 v[188:191], v179 offset0:76 offset1:78
	v_cvt_pk_bf16_f32 v194, v32, v33
	v_cvt_pk_bf16_f32 v195, v34, v35
	v_cvt_pk_bf16_f32 v196, v36, v37
	v_cvt_pk_bf16_f32 v197, v38, v39
	v_cvt_pk_bf16_f32 v198, v40, v41
	v_cvt_pk_bf16_f32 v199, v42, v43
	v_cvt_pk_bf16_f32 v200, v44, v45
	v_cvt_pk_bf16_f32 v201, v46, v47
	s_waitcnt lgkmcnt(2)
	v_mfma_f32_32x32x16_bf16 v[144:159], v[180:183], v[194:197], v[144:159]
	v_mfma_f32_32x32x16_bf16 v[128:143], v[164:167], v[194:197], v[128:143]
	s_waitcnt lgkmcnt(1)
	v_mfma_f32_32x32x16_bf16 v[144:159], v[184:187], v[198:201], v[144:159]
	s_waitcnt lgkmcnt(0)
	v_mfma_f32_32x32x16_bf16 v[128:143], v[188:191], v[198:201], v[128:143]
	ds_read2_b64 v[164:167], v179 offset0:80 offset1:82
	ds_read2_b64 v[180:183], v170 offset0:16 offset1:18
	ds_read2_b64 v[184:187], v170 offset0:20 offset1:22
	ds_read2_b64 v[188:191], v179 offset0:84 offset1:86
	v_cvt_pk_bf16_f32 v194, v16, v17
	v_cvt_pk_bf16_f32 v195, v18, v19
	v_cvt_pk_bf16_f32 v196, v20, v21
	v_cvt_pk_bf16_f32 v197, v22, v23
	v_cvt_pk_bf16_f32 v198, v24, v25
	v_cvt_pk_bf16_f32 v199, v26, v27
	v_cvt_pk_bf16_f32 v200, v28, v29
	v_cvt_pk_bf16_f32 v201, v30, v31
	s_waitcnt lgkmcnt(2)
	v_mfma_f32_32x32x16_bf16 v[144:159], v[180:183], v[194:197], v[144:159]
	v_mfma_f32_32x32x16_bf16 v[128:143], v[164:167], v[194:197], v[128:143]
	s_waitcnt lgkmcnt(1)
	v_mfma_f32_32x32x16_bf16 v[144:159], v[184:187], v[198:201], v[144:159]
	s_waitcnt lgkmcnt(0)
	v_mfma_f32_32x32x16_bf16 v[128:143], v[188:191], v[198:201], v[128:143]
	ds_read2_b64 v[164:167], v179 offset0:88 offset1:90
	ds_read2_b64 v[180:183], v170 offset0:24 offset1:26
	ds_read2_b64 v[184:187], v170 offset0:28 offset1:30
	ds_read2_b64 v[188:191], v179 offset0:92 offset1:94
	v_cvt_pk_bf16_f32 v194, v0, v1
	v_cvt_pk_bf16_f32 v195, v2, v3
	v_cvt_pk_bf16_f32 v196, v4, v5
	v_cvt_pk_bf16_f32 v197, v6, v7
	v_cvt_pk_bf16_f32 v198, v8, v9
	v_cvt_pk_bf16_f32 v199, v10, v11
	v_cvt_pk_bf16_f32 v200, v12, v13
	v_cvt_pk_bf16_f32 v201, v14, v15
	s_waitcnt lgkmcnt(2)
	v_mfma_f32_32x32x16_bf16 v[144:159], v[180:183], v[194:197], v[144:159]
	v_mfma_f32_32x32x16_bf16 v[128:143], v[164:167], v[194:197], v[128:143]
	s_waitcnt lgkmcnt(1)
	v_mfma_f32_32x32x16_bf16 v[144:159], v[184:187], v[198:201], v[144:159]
	s_waitcnt lgkmcnt(0)
	v_mfma_f32_32x32x16_bf16 v[128:143], v[188:191], v[198:201], v[128:143]
	ds_read2_b64 v[164:167], v179 offset0:96 offset1:98
	ds_read2_b64 v[180:183], v170 offset0:32 offset1:34
	ds_read2_b64 v[184:187], v170 offset0:36 offset1:38
	ds_read2_b64 v[188:191], v179 offset0:100 offset1:102
	v_cvt_pk_bf16_f32 v194, v64, v65
	v_cvt_pk_bf16_f32 v195, v66, v67
	v_cvt_pk_bf16_f32 v196, v68, v69
	v_cvt_pk_bf16_f32 v197, v70, v71
	v_cvt_pk_bf16_f32 v198, v72, v73
	v_cvt_pk_bf16_f32 v199, v74, v75
	v_cvt_pk_bf16_f32 v200, v76, v77
	v_cvt_pk_bf16_f32 v201, v78, v79
	s_waitcnt lgkmcnt(2)
	v_mfma_f32_32x32x16_bf16 v[144:159], v[180:183], v[194:197], v[144:159]
	v_mfma_f32_32x32x16_bf16 v[128:143], v[164:167], v[194:197], v[128:143]
	s_waitcnt lgkmcnt(1)
	v_mfma_f32_32x32x16_bf16 v[144:159], v[184:187], v[198:201], v[144:159]
	s_waitcnt lgkmcnt(0)
	v_mfma_f32_32x32x16_bf16 v[128:143], v[188:191], v[198:201], v[128:143]
	ds_read2_b64 v[164:167], v179 offset0:104 offset1:106
	ds_read2_b64 v[180:183], v170 offset0:40 offset1:42
	ds_read2_b64 v[184:187], v170 offset0:44 offset1:46
	ds_read2_b64 v[188:191], v179 offset0:108 offset1:110
	v_cvt_pk_bf16_f32 v194, v80, v81
	v_cvt_pk_bf16_f32 v195, v82, v83
	v_cvt_pk_bf16_f32 v196, v84, v85
	v_cvt_pk_bf16_f32 v197, v86, v87
	v_cvt_pk_bf16_f32 v198, v88, v89
	v_cvt_pk_bf16_f32 v199, v90, v91
	v_cvt_pk_bf16_f32 v200, v92, v93
	v_cvt_pk_bf16_f32 v201, v94, v95
	s_waitcnt lgkmcnt(2)
	v_mfma_f32_32x32x16_bf16 v[144:159], v[180:183], v[194:197], v[144:159]
	v_mfma_f32_32x32x16_bf16 v[128:143], v[164:167], v[194:197], v[128:143]
	s_waitcnt lgkmcnt(1)
	v_mfma_f32_32x32x16_bf16 v[144:159], v[184:187], v[198:201], v[144:159]
	s_waitcnt lgkmcnt(0)
	v_mfma_f32_32x32x16_bf16 v[128:143], v[188:191], v[198:201], v[128:143]
	ds_read2_b64 v[164:167], v179 offset0:112 offset1:114
	ds_read2_b64 v[180:183], v170 offset0:48 offset1:50
	ds_read2_b64 v[184:187], v170 offset0:52 offset1:54
	ds_read2_b64 v[188:191], v179 offset0:116 offset1:118
	v_cvt_pk_bf16_f32 v194, v96, v97
	v_cvt_pk_bf16_f32 v195, v98, v99
	v_cvt_pk_bf16_f32 v196, v100, v101
	v_cvt_pk_bf16_f32 v197, v102, v103
	v_cvt_pk_bf16_f32 v198, v104, v105
	v_cvt_pk_bf16_f32 v199, v106, v107
	v_cvt_pk_bf16_f32 v200, v108, v109
	v_cvt_pk_bf16_f32 v201, v110, v111
	s_waitcnt lgkmcnt(2)
	v_mfma_f32_32x32x16_bf16 v[144:159], v[180:183], v[194:197], v[144:159]
	v_mfma_f32_32x32x16_bf16 v[128:143], v[164:167], v[194:197], v[128:143]
	s_waitcnt lgkmcnt(1)
	v_mfma_f32_32x32x16_bf16 v[144:159], v[184:187], v[198:201], v[144:159]
	s_waitcnt lgkmcnt(0)
	v_mfma_f32_32x32x16_bf16 v[128:143], v[188:191], v[198:201], v[128:143]
	ds_read2_b64 v[164:167], v179 offset0:120 offset1:122
	ds_read2_b64 v[180:183], v170 offset0:56 offset1:58
	ds_read2_b64 v[184:187], v170 offset0:60 offset1:62
	ds_read2_b64 v[188:191], v179 offset0:124 offset1:126
	v_cvt_pk_bf16_f32 v194, v112, v113
	v_cvt_pk_bf16_f32 v195, v114, v115
	v_cvt_pk_bf16_f32 v196, v116, v117
	v_cvt_pk_bf16_f32 v197, v118, v119
	v_cvt_pk_bf16_f32 v198, v120, v121
	v_cvt_pk_bf16_f32 v199, v122, v123
	v_cvt_pk_bf16_f32 v200, v124, v125
	v_cvt_pk_bf16_f32 v201, v126, v127
	s_waitcnt lgkmcnt(2)
	v_mfma_f32_32x32x16_bf16 v[144:159], v[180:183], v[194:197], v[144:159]
	v_mfma_f32_32x32x16_bf16 v[128:143], v[164:167], v[194:197], v[128:143]
	s_waitcnt lgkmcnt(1)
	v_mfma_f32_32x32x16_bf16 v[144:159], v[184:187], v[198:201], v[144:159]
	s_waitcnt lgkmcnt(0)
	v_mfma_f32_32x32x16_bf16 v[128:143], v[188:191], v[198:201], v[128:143]
	v_mov_b32_e32 v179, v192
	s_barrier
; #define LAS __attribute__((address_space(3)))
; DI unsigned pk2(float a, float b) { f32x2 v = {a, b}; bf2_t r = __builtin_convertvector(v, bf2_t); return __builtin_bit_cast(unsigned, r); }
; DI int opq(int x) { asm volatile("" : "+v"(x)); return x; }
; DI bf16x8 join4(const s16x4& lo, const s16x4& hi) { return __builtin_shufflevector(lo, hi, 0, 1, 2, 3, 4, 5, 6, 7); }
; DI void phase_mlstm(const Params& p, unsigned char* shm, const int vb) {
;     ...
;                 const int lane = opq(threadIdx.x) & 63, l32 = lane & 31, hh = lane >> 5, q4 = (lane & 15) >> 2, p4 = lane & 3, blk = (lane >> 4) & 1;
; #pragma unroll
;                 for (int m = 0; m < 2; ++m)
; #pragma unroll
;                     for (int g = 0; g < 4; ++g) { const f32x4 d4 = *(const LAS f32x4*)(dec + 32 * m + 8 * g + 4 * hh);
; #pragma unroll
;                         for (int e = 0; e < 4; ++e) acc2[m][4 * g + e] *= d4[e]; }
;                 const int vb = VI + (8 * hh + q4) * RS + (32 * w + 16 * blk) * 2 + 8 * p4, sb = SMI + l32 * SMS + 16 * hh;
; #pragma unroll
;                 for (int kk = 0; kk < 4; ++kk) {
;                     const s16x4 lo = TRRD(lds + vb + 16 * kk * RS), hi = TRRD(lds + vb + 16 * kk * RS + 4 * RS);
;                     const bf16x8 bf = join4(lo, hi);
; #pragma unroll
;                     for (int m = 0; m < 2; ++m) { const bf16x8 af = *(const LAS bf16x8*)(lds + sb + 32 * m * SMS + 32 * kk); acc2[m] = MFMA32(af, bf, acc2[m]); }
;                 }
;                 const int hb = QI + 4 * hh * RS + (32 * w + l32) * 2;
; #pragma unroll
;                 for (int m = 0; m < 2; ++m)
; #pragma unroll
;                     for (int g = 0; g < 4; ++g) {
;                         const int rb = 32 * m + 8 * g;
;                         const f32x4 d4 = *(const LAS f32x4*)(dec + rb + 4 * hh), n4 = *(const LAS f32x4*)(qn + rb + 4 * hh), s4 = *(const LAS f32x4*)(rsum + rb + 4 * hh), f4 = *(const LAS f32x4*)(flr + rb + 4 * hh);
; #pragma unroll
;                         for (int e = 0; e < 4; ++e) {
;                             const float den = d4[e] * n4[e] + s4[e];
;                             const float val = acc2[m][4 * g + e] * __builtin_amdgcn_rcpf(fmaxf(fabsf(den), f4[e]));
;                             *(LAS bf16_t*)(lds + hb + (rb + e) * RS) = (bf16_t)(pk2(val, 0.f) & 0xffffu);
;                         }
;                     }
	s_mov_b32 s2, 0x12900
	v_bfe_u32 v193, v179, 5, 1
	v_lshl_add_u32 v199, v193, 4, 0
	v_add_u32_e32 v170, 0x1dd00, v199
	ds_read_b128 v[164:167], v170
	ds_read_b128 v[180:183], v170 offset:32
	ds_read_b128 v[184:187], v170 offset:64
	ds_read_b128 v[188:191], v170 offset:96
	v_bfe_u32 v198, v179, 2, 2
	s_waitcnt lgkmcnt(3)
	v_pk_mul_f32 v[146:147], v[146:147], v[166:167]
	s_waitcnt lgkmcnt(2)
	v_pk_mul_f32 v[148:149], v[148:149], v[180:181]
	s_waitcnt lgkmcnt(1)
	v_pk_mul_f32 v[152:153], v[152:153], v[184:185]
	s_waitcnt lgkmcnt(0)
	v_pk_mul_f32 v[156:157], v[156:157], v[188:189]
	v_pk_mul_f32 v[158:159], v[158:159], v[190:191]
	v_pk_mul_f32 v[154:155], v[154:155], v[186:187]
	v_pk_mul_f32 v[150:151], v[150:151], v[182:183]
	ds_read_b128 v[180:183], v170 offset:128
	ds_read_b128 v[184:187], v170 offset:160
	ds_read_b128 v[188:191], v170 offset:192
	ds_read_b128 v[194:197], v170 offset:224
	v_pk_mul_f32 v[144:145], v[144:145], v[164:165]
	s_waitcnt lgkmcnt(3)
	v_pk_mul_f32 v[128:129], v[128:129], v[180:181]
	v_lshl_or_b32 v180, v193, 3, v198
	v_and_or_b32 v181, v179, 16, s23
	s_waitcnt lgkmcnt(0)
	v_pk_mul_f32 v[140:141], v[140:141], v[194:195]
	v_and_b32_e32 v194, 31, v179
	v_mul_u32_u24_e32 v180, 0x210, v180
	v_lshlrev_b32_e32 v181, 1, v181
	v_lshlrev_b32_e32 v179, 3, v179
	v_and_b32_e32 v179, 24, v179
	v_add3_u32 v180, 0, v180, v181
	v_pk_mul_f32 v[130:131], v[130:131], v[182:183]
	v_mul_u32_u24_e32 v182, 0x90, v194
	v_add3_u32 v179, v180, v179, s2
	s_mov_b32 s2, 0x1ad00
	v_pk_mul_f32 v[136:137], v[136:137], v[188:189]
	v_pk_mul_f32 v[132:133], v[132:133], v[184:185]
	v_pk_mul_f32 v[138:139], v[138:139], v[190:191]
	v_pk_mul_f32 v[134:135], v[134:135], v[186:187]
	v_add3_u32 v195, v199, v182, s2
	ds_read_b64_tr_b16 v[180:181], v179
	ds_read_b64_tr_b16 v[182:183], v179 offset:2112
	ds_read_b128 v[184:187], v195
	ds_read_b128 v[188:191], v195 offset:32
	s_waitcnt lgkmcnt(1)
	v_mfma_f32_32x32x16_bf16 v[144:159], v[184:187], v[180:183], v[144:159]
	ds_read_b128 v[184:187], v195 offset:4608
	v_mul_f32_e64 v142, v142, v196
	v_mul_f32_e64 v143, v143, v197
	s_waitcnt lgkmcnt(0)
	s_nop 0
	v_mfma_f32_32x32x16_bf16 v[128:143], v[184:187], v[180:183], v[128:143]
	ds_read_b64_tr_b16 v[180:181], v179 offset:8448
	ds_read_b64_tr_b16 v[182:183], v179 offset:10560
	ds_read_b128 v[184:187], v195 offset:4640
	s_waitcnt lgkmcnt(1)
	v_mfma_f32_32x32x16_bf16 v[144:159], v[188:191], v[180:183], v[144:159]
	s_waitcnt lgkmcnt(0)
	v_mfma_f32_32x32x16_bf16 v[128:143], v[184:187], v[180:183], v[128:143]
	ds_read_b64_tr_b16 v[180:181], v179 offset:16896
	ds_read_b64_tr_b16 v[182:183], v179 offset:19008
	ds_read_b128 v[184:187], v195 offset:64
	s_waitcnt lgkmcnt(0)
	v_mfma_f32_32x32x16_bf16 v[144:159], v[184:187], v[180:183], v[144:159]
	ds_read_b128 v[184:187], v195 offset:4672
	s_waitcnt lgkmcnt(0)
	v_mfma_f32_32x32x16_bf16 v[128:143], v[184:187], v[180:183], v[128:143]
	ds_read_b64_tr_b16 v[180:181], v179 offset:25344
	ds_read_b64_tr_b16 v[182:183], v179 offset:27456
	ds_read_b128 v[184:187], v195 offset:96
	v_mul_u32_u24_e32 v179, 0x840, v193
	s_waitcnt lgkmcnt(0)
	v_mfma_f32_32x32x16_bf16 v[144:159], v[184:187], v[180:183], v[144:159]
	ds_read_b128 v[184:187], v195 offset:4704
	s_waitcnt lgkmcnt(0)
	v_mfma_f32_32x32x16_bf16 v[128:143], v[184:187], v[180:183], v[128:143]
	v_or_b32_e32 v180, s23, v194
	v_lshlrev_b32_e32 v183, 1, v180
	v_add_u32_e32 v180, 0x1d900, v199
	v_add_u32_e32 v181, 0x1da00, v199
	v_add_u32_e32 v182, 0x1de00, v199
	v_add3_u32 v179, 0, v179, v183
	v_and_b32_e32 v234, 63, v192
	v_lshlrev_b32_e32 v234, 2, v234
	v_add_u32_e32 v234, 0x1d900, v234
	ds_read_b32 v235, v234
	ds_read_b32 v236, v234 offset:256
	ds_read_b32 v237, v234 offset:1024
	ds_read_b32 v238, v234 offset:1280
	v_add_u32_e32 v239, 0x22000, v199
	s_waitcnt lgkmcnt(0)
	v_fma_f32 v237, v237, v235, v236
	v_max_f32_e32 v238, v238, v238
	v_max_f32_e64 v237, |v237|, v238
	v_rcp_f32_e32 v237, v237
	s_nop 0
	ds_write_b32 v234, v237 offset:18176
	s_waitcnt lgkmcnt(0)
	ds_read_b128 v[202:205], v239
	ds_read_b128 v[206:209], v239 offset:32
	ds_read_b128 v[210:213], v239 offset:64
	ds_read_b128 v[214:217], v239 offset:96
	ds_read_b128 v[218:221], v239 offset:128
	ds_read_b128 v[222:225], v239 offset:160
	ds_read_b128 v[226:229], v239 offset:192
	ds_read_b128 v[230:233], v239 offset:224
	v_and_b32_e32 v234, 1, v192
	v_cmp_eq_u32_e32 vcc, 0, v234
	v_mov_b32_e32 v237, 0x3020706
	v_mov_b32_e32 v236, 0x5040100
	v_cndmask_b32_e32 v237, v237, v236, vcc
	v_mul_u32_u24_e32 v238, 0x20e, v234
	v_add_u32_e32 v238, v179, v238
	s_waitcnt lgkmcnt(7)
	v_mul_f32_e32 v240, v144, v202
	v_mul_f32_e32 v241, v145, v203
	v_cvt_pk_bf16_f32 v242, v240, v241
	v_mul_f32_e32 v240, v146, v204
	v_mul_f32_e32 v241, v147, v205
	v_cvt_pk_bf16_f32 v243, v240, v241
	v_mov_b32_dpp v235, v242 quad_perm:[1,0,3,2] row_mask:0xf bank_mask:0xf
	v_perm_b32 v236, v235, v242, v237
	ds_write_b32 v238, v236
	v_mov_b32_dpp v235, v243 quad_perm:[1,0,3,2] row_mask:0xf bank_mask:0xf
	v_perm_b32 v236, v235, v243, v237
	ds_write_b32 v238, v236 offset:1056
	s_waitcnt lgkmcnt(8)
	v_mul_f32_e32 v240, v148, v206
	v_mul_f32_e32 v241, v149, v207
	v_cvt_pk_bf16_f32 v242, v240, v241
	v_mul_f32_e32 v240, v150, v208
	v_mul_f32_e32 v241, v151, v209
	v_cvt_pk_bf16_f32 v243, v240, v241
	v_mov_b32_dpp v235, v242 quad_perm:[1,0,3,2] row_mask:0xf bank_mask:0xf
	v_perm_b32 v236, v235, v242, v237
	ds_write_b32 v238, v236 offset:4224
	v_mov_b32_dpp v235, v243 quad_perm:[1,0,3,2] row_mask:0xf bank_mask:0xf
	v_perm_b32 v236, v235, v243, v237
	ds_write_b32 v238, v236 offset:5280
	s_waitcnt lgkmcnt(9)
; #define LAS __attribute__((address_space(3)))
; DI unsigned pk2(float a, float b) { f32x2 v = {a, b}; bf2_t r = __builtin_convertvector(v, bf2_t); return __builtin_bit_cast(unsigned, r); }
; DI int opq(int x) { asm volatile("" : "+v"(x)); return x; }
; DI u32x4 pack8f(const float (&f)[8]) { u32x4 r; r[0] = pk2(f[0], f[1]); r[1] = pk2(f[2], f[3]); r[2] = pk2(f[4], f[5]); r[3] = pk2(f[6], f[7]); return r; }
; DI bf16x8 join4(const s16x4& lo, const s16x4& hi) { return __builtin_shufflevector(lo, hi, 0, 1, 2, 3, 4, 5, 6, 7); }
; #define TRRD(ptr) __builtin_amdgcn_ds_read_tr16_b64_v4i16((LAS s16x4*)(ptr))
; DI void phase_mlstm(const Params& p, unsigned char* shm, const int vb) {
;     ...
;                         for (int e = 0; e < 4; ++e) {
;                             const float den = d4[e] * n4[e] + s4[e];
;                             const float val = acc2[m][4 * g + e] * __builtin_amdgcn_rcpf(fmaxf(fabsf(den), f4[e]));
;                             *(LAS bf16_t*)(lds + hb + (rb + e) * RS) = (bf16_t)(pk2(val, 0.f) & 0xffffu);
;                         }
;                     }
;     ...
;             {
;                 const int lane = opq(threadIdx.x) & 63, hh = lane >> 5, q4 = (lane & 15) >> 2, p4 = lane & 3, blk = (lane >> 4) & 1;
;                 const int tb = (8 * hh + q4) * RS + 32 * blk + 8 * p4;
;                 bf16x8 bw[4];
; #pragma unroll
;                 for (int kk = 0; kk < 4; ++kk) { const int voff = VI + tb + 64 * w + 16 * kk * RS;
;                     const bf16x8 raw = join4(TRRD(lds + voff), TRRD(lds + voff + 4 * RS));
;                     const f32x4 w0 = *(const LAS f32x4*)(wls + 16 * kk + 8 * hh), w1 = *(const LAS f32x4*)(wls + 16 * kk + 8 * hh + 4);
;                     float f[8]; unpack8(__builtin_bit_cast(u32x4, raw), f);
; #pragma unroll
;                     for (int e = 0; e < 4; ++e) { f[e] *= w0[e]; f[4 + e] *= w1[e]; }
;                     bw[kk] = __builtin_bit_cast(bf16x8, pack8f(f)); }
; #pragma unroll
;                 for (int ci = 0; ci < 8; ++ci) {
;                     bf16x8 ka[4];
; #pragma unroll
;                     for (int kk = 0; kk < 4; ++kk) { const int koff = KI + tb + 64 * ci + 16 * kk * RS; ka[kk] = join4(TRRD(lds + koff), TRRD(lds + koff + 4 * RS)); }
; #pragma unroll
;                     for (int e = 0; e < 16; ++e) C[ci][e] *= d_last;
	v_mul_f32_e32 v240, v152, v210
	v_mul_f32_e32 v241, v153, v211
	v_cvt_pk_bf16_f32 v242, v240, v241
	v_mul_f32_e32 v240, v154, v212
	v_mul_f32_e32 v241, v155, v213
	v_cvt_pk_bf16_f32 v243, v240, v241
	v_mov_b32_dpp v235, v242 quad_perm:[1,0,3,2] row_mask:0xf bank_mask:0xf
	v_perm_b32 v236, v235, v242, v237
	ds_write_b32 v238, v236 offset:8448
	v_mov_b32_dpp v235, v243 quad_perm:[1,0,3,2] row_mask:0xf bank_mask:0xf
	v_perm_b32 v236, v235, v243, v237
	ds_write_b32 v238, v236 offset:9504
	s_waitcnt lgkmcnt(10)
	v_mul_f32_e32 v240, v156, v214
	v_mul_f32_e32 v241, v157, v215
	v_cvt_pk_bf16_f32 v242, v240, v241
	v_mul_f32_e32 v240, v158, v216
	v_mul_f32_e32 v241, v159, v217
	v_cvt_pk_bf16_f32 v243, v240, v241
	v_mov_b32_dpp v235, v242 quad_perm:[1,0,3,2] row_mask:0xf bank_mask:0xf
	v_perm_b32 v236, v235, v242, v237
	ds_write_b32 v238, v236 offset:12672
	v_mov_b32_dpp v235, v243 quad_perm:[1,0,3,2] row_mask:0xf bank_mask:0xf
	v_perm_b32 v236, v235, v243, v237
	ds_write_b32 v238, v236 offset:13728
	s_waitcnt lgkmcnt(11)
	v_mul_f32_e32 v240, v128, v218
	v_mul_f32_e32 v241, v129, v219
	v_cvt_pk_bf16_f32 v242, v240, v241
	v_mul_f32_e32 v240, v130, v220
	v_mul_f32_e32 v241, v131, v221
	v_cvt_pk_bf16_f32 v243, v240, v241
	v_mov_b32_dpp v235, v242 quad_perm:[1,0,3,2] row_mask:0xf bank_mask:0xf
	v_perm_b32 v236, v235, v242, v237
	ds_write_b32 v238, v236 offset:16896
	v_mov_b32_dpp v235, v243 quad_perm:[1,0,3,2] row_mask:0xf bank_mask:0xf
	v_perm_b32 v236, v235, v243, v237
	ds_write_b32 v238, v236 offset:17952
	s_waitcnt lgkmcnt(12)
	v_mul_f32_e32 v240, v132, v222
	v_mul_f32_e32 v241, v133, v223
	v_cvt_pk_bf16_f32 v242, v240, v241
	v_mul_f32_e32 v240, v134, v224
	v_mul_f32_e32 v241, v135, v225
	v_cvt_pk_bf16_f32 v243, v240, v241
	v_mov_b32_dpp v235, v242 quad_perm:[1,0,3,2] row_mask:0xf bank_mask:0xf
	v_perm_b32 v236, v235, v242, v237
	ds_write_b32 v238, v236 offset:21120
	v_mov_b32_dpp v235, v243 quad_perm:[1,0,3,2] row_mask:0xf bank_mask:0xf
	v_perm_b32 v236, v235, v243, v237
	ds_write_b32 v238, v236 offset:22176
	s_waitcnt lgkmcnt(13)
	v_mul_f32_e32 v240, v136, v226
	v_mul_f32_e32 v241, v137, v227
	v_cvt_pk_bf16_f32 v242, v240, v241
	v_mul_f32_e32 v240, v138, v228
	v_mul_f32_e32 v241, v139, v229
	v_cvt_pk_bf16_f32 v243, v240, v241
	v_mov_b32_dpp v235, v242 quad_perm:[1,0,3,2] row_mask:0xf bank_mask:0xf
	v_perm_b32 v236, v235, v242, v237
	ds_write_b32 v238, v236 offset:25344
	v_mov_b32_dpp v235, v243 quad_perm:[1,0,3,2] row_mask:0xf bank_mask:0xf
	v_perm_b32 v236, v235, v243, v237
	ds_write_b32 v238, v236 offset:26400
	s_waitcnt lgkmcnt(14)
	v_mul_f32_e32 v240, v140, v230
	v_mul_f32_e32 v241, v141, v231
	v_cvt_pk_bf16_f32 v242, v240, v241
	v_mul_f32_e32 v240, v142, v232
	v_mul_f32_e32 v241, v143, v233
	v_cvt_pk_bf16_f32 v243, v240, v241
	v_mov_b32_dpp v235, v242 quad_perm:[1,0,3,2] row_mask:0xf bank_mask:0xf
	v_perm_b32 v236, v235, v242, v237
	ds_write_b32 v238, v236 offset:29568
	v_mov_b32_dpp v235, v243 quad_perm:[1,0,3,2] row_mask:0xf bank_mask:0xf
	v_perm_b32 v236, v235, v243, v237
	ds_write_b32 v238, v236 offset:30624
	v_mov_b32_e32 v128, v192
	v_pk_mul_f32 v[62:63], v[62:63], v[168:169] op_sel_hi:[1,0]
	v_lshrrev_b32_e32 v129, 2, v128
	v_lshlrev_b32_e32 v131, 3, v128
	v_and_b32_e32 v129, 11, v129
	v_lshlrev_b32_e32 v130, 1, v128
	v_and_b32_e32 v131, 24, v131
	v_mul_u32_u24_e32 v129, 0x210, v129
	v_and_b32_e32 v130, 32, v130
	v_add_u32_e32 v131, 0, v131
	v_add3_u32 v144, v131, v130, v129
	v_add_u32_e32 v129, s33, v144
	v_and_b32_e32 v128, 32, v128
	v_add_u32_e32 v145, 0x12900, v129
	v_add_u32_e32 v128, 0, v128
	v_add_u32_e32 v156, 0x1df00, v128
	ds_read_b64_tr_b16 v[136:137], v145
	ds_read_b128 v[128:131], v156
	ds_read_b128 v[132:135], v156 offset:16
	ds_read_b64_tr_b16 v[138:139], v145 offset:2112
	ds_read_b64_tr_b16 v[140:141], v145 offset:8448
	ds_read_b64_tr_b16 v[142:143], v145 offset:10560
	s_waitcnt lgkmcnt(5)
	v_lshlrev_b32_e32 v146, 16, v136
	v_and_b32_e32 v147, 0xffff0000, v136
	s_waitcnt lgkmcnt(4)
	v_pk_mul_f32 v[128:129], v[128:129], v[146:147]
	s_waitcnt lgkmcnt(2)
	v_lshlrev_b32_e32 v146, 16, v138
	v_and_b32_e32 v147, 0xffff0000, v138
	v_lshlrev_b32_e32 v136, 16, v137
	v_and_b32_e32 v137, 0xffff0000, v137
	v_pk_mul_f32 v[132:133], v[132:133], v[146:147]
	v_pk_mul_f32 v[130:131], v[130:131], v[136:137]
	v_lshlrev_b32_e32 v136, 16, v139
	v_and_b32_e32 v137, 0xffff0000, v139
	v_pk_mul_f32 v[136:137], v[134:135], v[136:137]
	v_cvt_pk_bf16_f32 v128, v128, v129
	v_cvt_pk_bf16_f32 v129, v130, v131
	v_cvt_pk_bf16_f32 v130, v132, v133
	ds_read_b128 v[132:135], v156 offset:64
	v_cvt_pk_bf16_f32 v131, v136, v137
	ds_read_b128 v[136:139], v156 offset:80
	s_waitcnt lgkmcnt(3)
	v_lshlrev_b32_e32 v146, 16, v140
	v_and_b32_e32 v147, 0xffff0000, v140
	v_lshlrev_b32_e32 v140, 16, v141
	v_and_b32_e32 v141, 0xffff0000, v141
	s_waitcnt lgkmcnt(1)
	v_pk_mul_f32 v[132:133], v[132:133], v[146:147]
	v_lshlrev_b32_e32 v146, 16, v142
	v_and_b32_e32 v147, 0xffff0000, v142
	v_pk_mul_f32 v[134:135], v[134:135], v[140:141]
	v_lshlrev_b32_e32 v140, 16, v143
	v_and_b32_e32 v141, 0xffff0000, v143
	s_waitcnt lgkmcnt(0)
	v_pk_mul_f32 v[136:137], v[136:137], v[146:147]
	v_pk_mul_f32 v[138:139], v[138:139], v[140:141]
	v_cvt_pk_bf16_f32 v132, v132, v133
	v_cvt_pk_bf16_f32 v133, v134, v135
	v_cvt_pk_bf16_f32 v134, v136, v137
	v_cvt_pk_bf16_f32 v135, v138, v139
	ds_read_b64_tr_b16 v[146:147], v145 offset:16896
	ds_read_b128 v[136:139], v156 offset:128
	ds_read_b128 v[140:143], v156 offset:144
	ds_read_b64_tr_b16 v[148:149], v145 offset:19008
	ds_read_b64_tr_b16 v[150:151], v145 offset:25344
	ds_read_b64_tr_b16 v[152:153], v145 offset:27456
	s_waitcnt lgkmcnt(5)
; #define LAS __attribute__((address_space(3)))
; DI u32x4 pack8f(const float (&f)[8]) { u32x4 r; r[0] = pk2(f[0], f[1]); r[1] = pk2(f[2], f[3]); r[2] = pk2(f[4], f[5]); r[3] = pk2(f[6], f[7]); return r; }
; DI bf16x8 join4(const s16x4& lo, const s16x4& hi) { return __builtin_shufflevector(lo, hi, 0, 1, 2, 3, 4, 5, 6, 7); }
; #define MFMA32(a, b, c) __builtin_amdgcn_mfma_f32_32x32x16_bf16((a), (b), (c), 0, 0, 0)
; #define TRRD(ptr) __builtin_amdgcn_ds_read_tr16_b64_v4i16((LAS s16x4*)(ptr))
; DI void phase_mlstm(const Params& p, unsigned char* shm, const int vb) {
;     ...
;                 for (int kk = 0; kk < 4; ++kk) { const int voff = VI + tb + 64 * w + 16 * kk * RS;
;                     const bf16x8 raw = join4(TRRD(lds + voff), TRRD(lds + voff + 4 * RS));
;                     const f32x4 w0 = *(const LAS f32x4*)(wls + 16 * kk + 8 * hh), w1 = *(const LAS f32x4*)(wls + 16 * kk + 8 * hh + 4);
;                     float f[8]; unpack8(__builtin_bit_cast(u32x4, raw), f);
; #pragma unroll
;                     for (int e = 0; e < 4; ++e) { f[e] *= w0[e]; f[4 + e] *= w1[e]; }
;                     bw[kk] = __builtin_bit_cast(bf16x8, pack8f(f)); }
; #pragma unroll
;                 for (int ci = 0; ci < 8; ++ci) {
;                     bf16x8 ka[4];
; #pragma unroll
;                     for (int kk = 0; kk < 4; ++kk) { const int koff = KI + tb + 64 * ci + 16 * kk * RS; ka[kk] = join4(TRRD(lds + koff), TRRD(lds + koff + 4 * RS)); }
; #pragma unroll
;                     for (int e = 0; e < 16; ++e) C[ci][e] *= d_last;
;                     __builtin_amdgcn_sched_barrier(0);
; #pragma unroll
;                     for (int kk = 0; kk < 4; ++kk) C[ci] = MFMA32(ka[kk], bw[kk], C[ci]);
;                     __builtin_amdgcn_sched_barrier(0);
;                 }
	v_lshlrev_b32_e32 v154, 16, v146
	v_and_b32_e32 v155, 0xffff0000, v146
	s_waitcnt lgkmcnt(4)
	v_pk_mul_f32 v[136:137], v[136:137], v[154:155]
	s_waitcnt lgkmcnt(2)
	v_lshlrev_b32_e32 v154, 16, v148
	v_and_b32_e32 v155, 0xffff0000, v148
	v_lshlrev_b32_e32 v146, 16, v147
	v_and_b32_e32 v147, 0xffff0000, v147
	v_pk_mul_f32 v[140:141], v[140:141], v[154:155]
	v_pk_mul_f32 v[138:139], v[138:139], v[146:147]
	v_lshlrev_b32_e32 v146, 16, v149
	v_and_b32_e32 v147, 0xffff0000, v149
	v_pk_mul_f32 v[146:147], v[142:143], v[146:147]
	v_cvt_pk_bf16_f32 v136, v136, v137
	v_cvt_pk_bf16_f32 v137, v138, v139
	v_cvt_pk_bf16_f32 v138, v140, v141
	ds_read_b128 v[140:143], v156 offset:192
	v_cvt_pk_bf16_f32 v139, v146, v147
	ds_read_b128 v[146:149], v156 offset:208
	s_waitcnt lgkmcnt(3)
	v_lshlrev_b32_e32 v154, 16, v150
	v_and_b32_e32 v155, 0xffff0000, v150
	v_lshlrev_b32_e32 v150, 16, v151
	v_and_b32_e32 v151, 0xffff0000, v151
	s_waitcnt lgkmcnt(1)
	v_pk_mul_f32 v[140:141], v[140:141], v[154:155]
	v_lshlrev_b32_e32 v154, 16, v152
	v_and_b32_e32 v155, 0xffff0000, v152
	v_pk_mul_f32 v[142:143], v[142:143], v[150:151]
	v_lshlrev_b32_e32 v150, 16, v153
	v_and_b32_e32 v151, 0xffff0000, v153
	s_waitcnt lgkmcnt(0)
	v_pk_mul_f32 v[146:147], v[146:147], v[154:155]
	v_pk_mul_f32 v[148:149], v[148:149], v[150:151]
	v_cvt_pk_bf16_f32 v140, v140, v141
	v_cvt_pk_bf16_f32 v141, v142, v143
	v_cvt_pk_bf16_f32 v142, v146, v147
	v_cvt_pk_bf16_f32 v143, v148, v149
	ds_read_b64_tr_b16 v[146:147], v144 offset:33792
	ds_read_b64_tr_b16 v[148:149], v144 offset:35904
	ds_read_b64_tr_b16 v[150:151], v144 offset:42240
	ds_read_b64_tr_b16 v[152:153], v144 offset:44352
	ds_read_b64_tr_b16 v[154:155], v144 offset:50688
	ds_read_b64_tr_b16 v[156:157], v144 offset:52800
	ds_read_b64_tr_b16 v[164:165], v144 offset:59136
	ds_read_b64_tr_b16 v[166:167], v144 offset:61248
	v_pk_mul_f32 v[60:61], v[60:61], v[168:169] op_sel_hi:[1,0]
	v_pk_mul_f32 v[58:59], v[58:59], v[168:169] op_sel_hi:[1,0]
	v_pk_mul_f32 v[56:57], v[56:57], v[168:169] op_sel_hi:[1,0]
	v_pk_mul_f32 v[54:55], v[54:55], v[168:169] op_sel_hi:[1,0]
	v_pk_mul_f32 v[52:53], v[52:53], v[168:169] op_sel_hi:[1,0]
	v_pk_mul_f32 v[50:51], v[50:51], v[168:169] op_sel_hi:[1,0]
	v_pk_mul_f32 v[48:49], v[48:49], v[168:169] op_sel_hi:[1,0]
	s_waitcnt lgkmcnt(6)
	s_nop 0
	v_mfma_f32_32x32x16_bf16 v[48:63], v[146:149], v[128:131], v[48:63]
	s_waitcnt lgkmcnt(4)
	v_mfma_f32_32x32x16_bf16 v[48:63], v[150:153], v[132:135], v[48:63]
	s_waitcnt lgkmcnt(2)
	v_mfma_f32_32x32x16_bf16 v[48:63], v[154:157], v[136:139], v[48:63]
	s_waitcnt lgkmcnt(0)
	v_mfma_f32_32x32x16_bf16 v[48:63], v[164:167], v[140:143], v[48:63]
	ds_read_b64_tr_b16 v[146:147], v144 offset:33856
	ds_read_b64_tr_b16 v[148:149], v144 offset:35968
	ds_read_b64_tr_b16 v[150:151], v144 offset:42304
	ds_read_b64_tr_b16 v[152:153], v144 offset:44416
	ds_read_b64_tr_b16 v[154:155], v144 offset:50752
	ds_read_b64_tr_b16 v[156:157], v144 offset:52864
	ds_read_b64_tr_b16 v[164:165], v144 offset:59200
	ds_read_b64_tr_b16 v[166:167], v144 offset:61312
	v_pk_mul_f32 v[46:47], v[46:47], v[168:169] op_sel_hi:[1,0]
	v_pk_mul_f32 v[44:45], v[44:45], v[168:169] op_sel_hi:[1,0]
	v_pk_mul_f32 v[42:43], v[42:43], v[168:169] op_sel_hi:[1,0]
	v_pk_mul_f32 v[40:41], v[40:41], v[168:169] op_sel_hi:[1,0]
	v_pk_mul_f32 v[38:39], v[38:39], v[168:169] op_sel_hi:[1,0]
	v_pk_mul_f32 v[36:37], v[36:37], v[168:169] op_sel_hi:[1,0]
	v_pk_mul_f32 v[34:35], v[34:35], v[168:169] op_sel_hi:[1,0]
	v_pk_mul_f32 v[32:33], v[32:33], v[168:169] op_sel_hi:[1,0]
	s_waitcnt lgkmcnt(6)
	s_nop 0
	v_mfma_f32_32x32x16_bf16 v[32:47], v[146:149], v[128:131], v[32:47]
	s_waitcnt lgkmcnt(4)
	v_mfma_f32_32x32x16_bf16 v[32:47], v[150:153], v[132:135], v[32:47]
	s_waitcnt lgkmcnt(2)
	v_mfma_f32_32x32x16_bf16 v[32:47], v[154:157], v[136:139], v[32:47]
	s_waitcnt lgkmcnt(0)
	v_mfma_f32_32x32x16_bf16 v[32:47], v[164:167], v[140:143], v[32:47]
	ds_read_b64_tr_b16 v[146:147], v144 offset:33920
	ds_read_b64_tr_b16 v[148:149], v144 offset:36032
	ds_read_b64_tr_b16 v[150:151], v144 offset:42368
	ds_read_b64_tr_b16 v[152:153], v144 offset:44480
	ds_read_b64_tr_b16 v[154:155], v144 offset:50816
	ds_read_b64_tr_b16 v[156:157], v144 offset:52928
	ds_read_b64_tr_b16 v[164:165], v144 offset:59264
	ds_read_b64_tr_b16 v[166:167], v144 offset:61376
	v_pk_mul_f32 v[30:31], v[30:31], v[168:169] op_sel_hi:[1,0]
	v_pk_mul_f32 v[28:29], v[28:29], v[168:169] op_sel_hi:[1,0]
	v_pk_mul_f32 v[26:27], v[26:27], v[168:169] op_sel_hi:[1,0]
	v_pk_mul_f32 v[24:25], v[24:25], v[168:169] op_sel_hi:[1,0]
	v_pk_mul_f32 v[22:23], v[22:23], v[168:169] op_sel_hi:[1,0]
	v_pk_mul_f32 v[20:21], v[20:21], v[168:169] op_sel_hi:[1,0]
	v_pk_mul_f32 v[18:19], v[18:19], v[168:169] op_sel_hi:[1,0]
	v_pk_mul_f32 v[16:17], v[16:17], v[168:169] op_sel_hi:[1,0]
	s_waitcnt lgkmcnt(6)
	s_nop 0
	v_mfma_f32_32x32x16_bf16 v[16:31], v[146:149], v[128:131], v[16:31]
	s_waitcnt lgkmcnt(4)
	v_mfma_f32_32x32x16_bf16 v[16:31], v[150:153], v[132:135], v[16:31]
	s_waitcnt lgkmcnt(2)
	v_mfma_f32_32x32x16_bf16 v[16:31], v[154:157], v[136:139], v[16:31]
	s_waitcnt lgkmcnt(0)
	v_mfma_f32_32x32x16_bf16 v[16:31], v[164:167], v[140:143], v[16:31]
	ds_read_b64_tr_b16 v[146:147], v144 offset:33984
	ds_read_b64_tr_b16 v[148:149], v144 offset:36096
	ds_read_b64_tr_b16 v[150:151], v144 offset:42432
	ds_read_b64_tr_b16 v[152:153], v144 offset:44544
	ds_read_b64_tr_b16 v[154:155], v144 offset:50880
	ds_read_b64_tr_b16 v[156:157], v144 offset:52992
	ds_read_b64_tr_b16 v[164:165], v144 offset:59328
	ds_read_b64_tr_b16 v[166:167], v144 offset:61440
	v_pk_mul_f32 v[14:15], v[14:15], v[168:169] op_sel_hi:[1,0]
	v_pk_mul_f32 v[12:13], v[12:13], v[168:169] op_sel_hi:[1,0]
	v_pk_mul_f32 v[10:11], v[10:11], v[168:169] op_sel_hi:[1,0]
	v_pk_mul_f32 v[8:9], v[8:9], v[168:169] op_sel_hi:[1,0]
	v_pk_mul_f32 v[6:7], v[6:7], v[168:169] op_sel_hi:[1,0]
	v_pk_mul_f32 v[4:5], v[4:5], v[168:169] op_sel_hi:[1,0]
	v_pk_mul_f32 v[2:3], v[2:3], v[168:169] op_sel_hi:[1,0]
	v_pk_mul_f32 v[0:1], v[0:1], v[168:169] op_sel_hi:[1,0]
	s_waitcnt lgkmcnt(6)
; #define LAS __attribute__((address_space(3)))
; DI int opq(int x) { asm volatile("" : "+v"(x)); return x; }
; DI bf16x8 join4(const s16x4& lo, const s16x4& hi) { return __builtin_shufflevector(lo, hi, 0, 1, 2, 3, 4, 5, 6, 7); }
; #define MFMA32(a, b, c) __builtin_amdgcn_mfma_f32_32x32x16_bf16((a), (b), (c), 0, 0, 0)
; #define TRRD(ptr) __builtin_amdgcn_ds_read_tr16_b64_v4i16((LAS s16x4*)(ptr))
; DI void phase_mlstm(const Params& p, unsigned char* shm, const int vb) {
;     ...
; #pragma unroll
;                 for (int ci = 0; ci < 8; ++ci) {
;                     bf16x8 ka[4];
; #pragma unroll
;                     for (int kk = 0; kk < 4; ++kk) { const int koff = KI + tb + 64 * ci + 16 * kk * RS; ka[kk] = join4(TRRD(lds + koff), TRRD(lds + koff + 4 * RS)); }
; #pragma unroll
;                     for (int e = 0; e < 16; ++e) C[ci][e] *= d_last;
;                     __builtin_amdgcn_sched_barrier(0);
; #pragma unroll
;                     for (int kk = 0; kk < 4; ++kk) C[ci] = MFMA32(ka[kk], bw[kk], C[ci]);
;                     __builtin_amdgcn_sched_barrier(0);
;                 }
;             }
;             __syncthreads();
;             {
;                 const int tid = opq(threadIdx.x), r4 = tid >> 5, cgp = tid & 31;
;                 bf16_t* hp = H + (size_t)(t0 + r4) * 2048 + h * 512 + half * 256 + 8 * cgp;
; #pragma unroll
;                 for (int i = 0; i < 4; ++i) *(u32x4*)(hp + (size_t)i * 16 * 2048) = *(const LAS u32x4*)(lds + QI + (r4 + 16 * i) * RS + 16 * cgp);
;             }
	s_nop 0
	v_mfma_f32_32x32x16_bf16 v[0:15], v[146:149], v[128:131], v[0:15]
	s_waitcnt lgkmcnt(4)
	v_mfma_f32_32x32x16_bf16 v[0:15], v[150:153], v[132:135], v[0:15]
	s_waitcnt lgkmcnt(2)
	v_mfma_f32_32x32x16_bf16 v[0:15], v[154:157], v[136:139], v[0:15]
	s_waitcnt lgkmcnt(0)
	v_mfma_f32_32x32x16_bf16 v[0:15], v[164:167], v[140:143], v[0:15]
	ds_read_b64_tr_b16 v[146:147], v144 offset:34048
	ds_read_b64_tr_b16 v[148:149], v144 offset:36160
	ds_read_b64_tr_b16 v[150:151], v144 offset:42496
	ds_read_b64_tr_b16 v[152:153], v144 offset:44608
	ds_read_b64_tr_b16 v[154:155], v144 offset:50944
	ds_read_b64_tr_b16 v[156:157], v144 offset:53056
	ds_read_b64_tr_b16 v[164:165], v144 offset:59392
	ds_read_b64_tr_b16 v[166:167], v144 offset:61504
	v_pk_mul_f32 v[78:79], v[78:79], v[168:169] op_sel_hi:[1,0]
	v_pk_mul_f32 v[76:77], v[76:77], v[168:169] op_sel_hi:[1,0]
	v_pk_mul_f32 v[74:75], v[74:75], v[168:169] op_sel_hi:[1,0]
	v_pk_mul_f32 v[72:73], v[72:73], v[168:169] op_sel_hi:[1,0]
	v_pk_mul_f32 v[70:71], v[70:71], v[168:169] op_sel_hi:[1,0]
	v_pk_mul_f32 v[68:69], v[68:69], v[168:169] op_sel_hi:[1,0]
	v_pk_mul_f32 v[66:67], v[66:67], v[168:169] op_sel_hi:[1,0]
	v_pk_mul_f32 v[64:65], v[64:65], v[168:169] op_sel_hi:[1,0]
	s_waitcnt lgkmcnt(6)
	s_nop 0
	v_mfma_f32_32x32x16_bf16 v[64:79], v[146:149], v[128:131], v[64:79]
	s_waitcnt lgkmcnt(4)
	v_mfma_f32_32x32x16_bf16 v[64:79], v[150:153], v[132:135], v[64:79]
	s_waitcnt lgkmcnt(2)
	v_mfma_f32_32x32x16_bf16 v[64:79], v[154:157], v[136:139], v[64:79]
	s_waitcnt lgkmcnt(0)
	v_mfma_f32_32x32x16_bf16 v[64:79], v[164:167], v[140:143], v[64:79]
	ds_read_b64_tr_b16 v[146:147], v144 offset:34112
	ds_read_b64_tr_b16 v[148:149], v144 offset:36224
	ds_read_b64_tr_b16 v[150:151], v144 offset:42560
	ds_read_b64_tr_b16 v[152:153], v144 offset:44672
	ds_read_b64_tr_b16 v[154:155], v144 offset:51008
	ds_read_b64_tr_b16 v[156:157], v144 offset:53120
	ds_read_b64_tr_b16 v[164:165], v144 offset:59456
	ds_read_b64_tr_b16 v[166:167], v144 offset:61568
	v_pk_mul_f32 v[94:95], v[94:95], v[168:169] op_sel_hi:[1,0]
	v_pk_mul_f32 v[92:93], v[92:93], v[168:169] op_sel_hi:[1,0]
	v_pk_mul_f32 v[90:91], v[90:91], v[168:169] op_sel_hi:[1,0]
	v_pk_mul_f32 v[88:89], v[88:89], v[168:169] op_sel_hi:[1,0]
	v_pk_mul_f32 v[86:87], v[86:87], v[168:169] op_sel_hi:[1,0]
	v_pk_mul_f32 v[84:85], v[84:85], v[168:169] op_sel_hi:[1,0]
	v_pk_mul_f32 v[82:83], v[82:83], v[168:169] op_sel_hi:[1,0]
	v_pk_mul_f32 v[80:81], v[80:81], v[168:169] op_sel_hi:[1,0]
	s_waitcnt lgkmcnt(6)
	s_nop 0
	v_mfma_f32_32x32x16_bf16 v[80:95], v[146:149], v[128:131], v[80:95]
	s_waitcnt lgkmcnt(4)
	v_mfma_f32_32x32x16_bf16 v[80:95], v[150:153], v[132:135], v[80:95]
	s_waitcnt lgkmcnt(2)
	v_mfma_f32_32x32x16_bf16 v[80:95], v[154:157], v[136:139], v[80:95]
	s_waitcnt lgkmcnt(0)
	v_mfma_f32_32x32x16_bf16 v[80:95], v[164:167], v[140:143], v[80:95]
	ds_read_b64_tr_b16 v[146:147], v144 offset:34176
	ds_read_b64_tr_b16 v[148:149], v144 offset:36288
	ds_read_b64_tr_b16 v[150:151], v144 offset:42624
	ds_read_b64_tr_b16 v[152:153], v144 offset:44736
	ds_read_b64_tr_b16 v[154:155], v144 offset:51072
	ds_read_b64_tr_b16 v[156:157], v144 offset:53184
	ds_read_b64_tr_b16 v[164:165], v144 offset:59520
	ds_read_b64_tr_b16 v[166:167], v144 offset:61632
	v_pk_mul_f32 v[110:111], v[110:111], v[168:169] op_sel_hi:[1,0]
	v_pk_mul_f32 v[108:109], v[108:109], v[168:169] op_sel_hi:[1,0]
	v_pk_mul_f32 v[106:107], v[106:107], v[168:169] op_sel_hi:[1,0]
	v_pk_mul_f32 v[104:105], v[104:105], v[168:169] op_sel_hi:[1,0]
	v_pk_mul_f32 v[102:103], v[102:103], v[168:169] op_sel_hi:[1,0]
	v_pk_mul_f32 v[100:101], v[100:101], v[168:169] op_sel_hi:[1,0]
	v_pk_mul_f32 v[98:99], v[98:99], v[168:169] op_sel_hi:[1,0]
	v_pk_mul_f32 v[96:97], v[96:97], v[168:169] op_sel_hi:[1,0]
	s_waitcnt lgkmcnt(6)
	s_nop 0
	v_mfma_f32_32x32x16_bf16 v[96:111], v[146:149], v[128:131], v[96:111]
	s_waitcnt lgkmcnt(4)
	v_mfma_f32_32x32x16_bf16 v[96:111], v[150:153], v[132:135], v[96:111]
	s_waitcnt lgkmcnt(2)
	v_mfma_f32_32x32x16_bf16 v[96:111], v[154:157], v[136:139], v[96:111]
	s_waitcnt lgkmcnt(0)
	v_mfma_f32_32x32x16_bf16 v[96:111], v[164:167], v[140:143], v[96:111]
	ds_read_b64_tr_b16 v[146:147], v144 offset:34240
	ds_read_b64_tr_b16 v[148:149], v144 offset:36352
	ds_read_b64_tr_b16 v[150:151], v144 offset:42688
	ds_read_b64_tr_b16 v[152:153], v144 offset:44800
	ds_read_b64_tr_b16 v[154:155], v144 offset:51136
	ds_read_b64_tr_b16 v[156:157], v144 offset:53248
	ds_read_b64_tr_b16 v[164:165], v144 offset:59584
	ds_read_b64_tr_b16 v[166:167], v144 offset:61696
	v_pk_mul_f32 v[126:127], v[126:127], v[168:169] op_sel_hi:[1,0]
	v_pk_mul_f32 v[124:125], v[124:125], v[168:169] op_sel_hi:[1,0]
	v_pk_mul_f32 v[122:123], v[122:123], v[168:169] op_sel_hi:[1,0]
	v_pk_mul_f32 v[120:121], v[120:121], v[168:169] op_sel_hi:[1,0]
	v_pk_mul_f32 v[118:119], v[118:119], v[168:169] op_sel_hi:[1,0]
	v_pk_mul_f32 v[116:117], v[116:117], v[168:169] op_sel_hi:[1,0]
	v_pk_mul_f32 v[114:115], v[114:115], v[168:169] op_sel_hi:[1,0]
	v_pk_mul_f32 v[112:113], v[112:113], v[168:169] op_sel_hi:[1,0]
	s_waitcnt lgkmcnt(6)
	s_nop 0
	v_mfma_f32_32x32x16_bf16 v[112:127], v[146:149], v[128:131], v[112:127]
	s_waitcnt lgkmcnt(4)
	v_mfma_f32_32x32x16_bf16 v[112:127], v[150:153], v[132:135], v[112:127]
	s_waitcnt lgkmcnt(2)
	v_mfma_f32_32x32x16_bf16 v[112:127], v[154:157], v[136:139], v[112:127]
	s_waitcnt lgkmcnt(0)
	v_mfma_f32_32x32x16_bf16 v[112:127], v[164:167], v[140:143], v[112:127]
	v_mov_b32_e32 v132, v192
	s_barrier
	s_add_u32 s76, s76, 0x100
	v_ashrrev_i32_e32 v128, 5, v132
	v_ashrrev_i32_e32 v129, 31, v128
	v_lshl_add_u64 v[130:131], s[74:75], 0, v[128:129]
	v_lshlrev_b32_e32 v129, 4, v132
	v_lshlrev_b64 v[130:131], 12, v[130:131]
	v_and_b32_e32 v168, 0x1f0, v129
	v_mul_lo_u32 v128, v128, s61
	v_lshl_add_u64 v[130:131], s[70:71], 0, v[130:131]
	v_add3_u32 v136, 0, v168, v128
	v_lshl_add_u64 v[132:133], v[130:131], 0, v[168:169]
	ds_read_b128 v[128:131], v136
	v_add_co_u32_e32 v134, vcc, s97, v132
	s_addc_u32 s77, s77, 0
	s_nop 0
	v_addc_co_u32_e32 v135, vcc, 0, v133, vcc
	s_waitcnt lgkmcnt(0)
	global_store_dwordx4 v[132:133], v[128:131], off
	ds_read_b128 v[128:131], v136 offset:8448
	s_add_u32 s72, s72, 64
	s_addc_u32 s73, s73, 0
	s_add_u32 s74, s74, 64
	s_addc_u32 s75, s75, 0
	s_waitcnt lgkmcnt(0)
	global_store_dwordx4 v[134:135], v[128:131], off
	ds_read_b128 v[128:131], v136 offset:16896
	v_add_co_u32_e32 v134, vcc, s79, v132
	s_cmpk_eq_i32 s76, 0x2000
	s_nop 0
	v_addc_co_u32_e32 v135, vcc, 0, v133, vcc
	s_waitcnt lgkmcnt(0)
	global_store_dwordx4 v[134:135], v[128:131], off
	ds_read_b128 v[128:131], v136 offset:25344
	v_add_co_u32_e32 v132, vcc, s82, v132
	s_nop 1
	v_addc_co_u32_e32 v133, vcc, 0, v133, vcc
	s_waitcnt lgkmcnt(0)
	global_store_dwordx4 v[132:133], v[128:131], off
	s_cbranch_scc1 .LBB0_386
